# K-loop loader segments at s_setprio 2 (MFMA blocks stay at 1)
# speedup vs baseline: 1.0045x; 1.0045x over previous
; #define PG8_STAGE(bufoff, gbase, voff, h64) do { \
;         __builtin_amdgcn_global_load_lds((const unsigned*)((const char*)(gbase) + (voff)), (LAS unsigned*)(lds + (bufoff) + ldsw), 16, 0, 0); \
;         __builtin_amdgcn_global_load_lds((const unsigned*)((const char*)(gbase) + (h64) + (voff)), (LAS unsigned*)(lds + (bufoff) + ldsw + 8192), 16, 0, 0); } while (0)
; #define PG8_LDA(dst, b, h) do { _Pragma("unroll") for (int m = 0; m < 4; ++m) { dst[m].lo = *(const LAS f16x8*)(lds + PG8_SA(b, h) + aoff + m * 2048); dst[m].hi = *(const LAS f16x8*)(lds + PG8_SA(b, h) + aoff + m * 2048 + 1024); } } while (0)
; #define PG8_LDB(dst, b, h) do { _Pragma("unroll") for (int n = 0; n < 2; ++n) { dst[n].lo = *(const LAS f16x8*)(lds + PG8_SB(b, h) + boff + n * 2048); dst[n].hi = *(const LAS f16x8*)(lds + PG8_SB(b, h) + boff + n * 2048 + 1024); } } while (0)
; #define PG8_WAIT_V(n) asm volatile("s_waitcnt vmcnt(" #n ")" ::: "memory")
; #define PG8_WAIT_L(n) asm volatile("s_waitcnt lgkmcnt(" #n ")" ::: "memory")
; #define PG8_BAR __builtin_amdgcn_s_barrier()
; #define PG8_SCHED __builtin_amdgcn_sched_barrier(0)
; template <bool F8 = false, class Sched, class Epi>
; __device__ __forceinline__ void gemm_phase(LAS unsigned char* lds, const Sched& S, const Epi& E) {
;     ...
;             PG8_LDB(B0, 0, 0); PG8_LDB(B1, 0, 1); PG8_SCHED; PG8_LDA(At, 0, 0); PG8_STAGE(PG8_SA(1, 1), a1 + chs, cvA, ch64);
;             PG8_WAIT_V(8); PG8_WAIT_L(0); PG8_BAR; PG8_MMA(0, 0, At, B0); PG8_MMA(0, 1, At, B1); PG8_BAR; PG8_SCHED;
;             PG8_LDA(At, 0, 1); PG8_STAGE(PG8_SB(0, 0), b2, vB2, h2); PG8_STAGE(PG8_SB(0, 1), b2 + bhs2, vB2, h2); PG8_STAGE(PG8_SA(0, 0), a2, vA2, h2);
;             PG8_WAIT_V(8); PG8_WAIT_L(0); PG8_BAR; PG8_MMA(1, 0, At, B0); PG8_MMA(1, 1, At, B1); PG8_BAR; PG8_SCHED;
.LBB0_73:
	s_add_u32 s24, s12, s8
	s_addc_u32 s25, s13, s9
	s_add_u32 s26, s24, 0x100
	s_addc_u32 s27, s25, 0
	s_add_u32 s36, s71, s8
	s_addc_u32 s68, s72, s9
	s_cmpk_eq_i32 s8, 0x300
	s_cselect_b64 vcc, -1, 0
	s_and_b64 s[24:25], vcc, exec
	s_cselect_b32 s25, s73, s27
	s_cselect_b32 s24, s74, s26
	s_cselect_b32 s27, s75, s68
	s_cselect_b32 s26, s80, s36
	s_add_i32 s36, 0, 0x10000
	s_add_i32 s68, 0, 0x14000
	v_add_u32_e32 v0, s36, v163
	v_add_u32_e32 v12, s68, v163
	ds_read_b128 v[16:19], v0
	ds_read_b128 v[20:23], v0 offset:1024
	ds_read_b128 v[24:27], v0 offset:2048
	ds_read_b128 v[28:31], v0 offset:3072
	ds_read_b128 v[0:3], v12
	ds_read_b128 v[4:7], v12 offset:1024
	ds_read_b128 v[8:11], v12 offset:2048
	ds_read_b128 v[12:15], v12 offset:3072
	v_cndmask_b32_e32 v32, v164, v166, vcc
	v_cndmask_b32_e32 v172, v162, v175, vcc
	v_lshl_add_u64 v[170:171], v[168:169], 0, s[8:9]
	v_lshl_add_u64 v[192:193], v[170:171], 0, s[58:59]
	s_add_i32 m0, s31, 0xc000
	ds_read_b128 v[176:179], v174
	ds_read_b128 v[180:183], v174 offset:1024
	ds_read_b128 v[184:187], v174 offset:2048
	ds_read_b128 v[188:191], v174 offset:3072
	ds_read_b128 v[198:201], v174 offset:4096
	ds_read_b128 v[202:205], v174 offset:5120
	ds_read_b128 v[206:209], v174 offset:6144
	ds_read_b128 v[210:213], v174 offset:7168
	global_load_lds_dwordx4 v[192:193], off
	v_lshl_add_u64 v[170:171], v[170:171], 0, s[76:77]
	s_add_i32 m0, s31, 0xe000
	s_nop 0
	global_load_lds_dwordx4 v[170:171], off
	s_waitcnt vmcnt(8)
	s_waitcnt lgkmcnt(0)
	s_barrier
	s_setprio 1
	s_waitcnt lgkmcnt(0)
	v_mfma_scale_f32_16x16x128_f8f6f4 v[158:161], v[16:23], v[176:183], v[158:161], v220, v221 op_sel_hi:[0,0,0]
	v_mfma_scale_f32_16x16x128_f8f6f4 v[154:157], v[24:31], v[176:183], v[154:157], v220, v221 op_sel_hi:[0,0,0]
	v_mfma_scale_f32_16x16x128_f8f6f4 v[150:153], v[16:23], v[184:191], v[150:153], v220, v221 op_sel_hi:[0,0,0]
	v_mfma_scale_f32_16x16x128_f8f6f4 v[146:149], v[24:31], v[184:191], v[146:149], v220, v221 op_sel_hi:[0,0,0]
	v_mfma_scale_f32_16x16x128_f8f6f4 v[142:145], v[16:23], v[198:205], v[142:145], v220, v221 op_sel_hi:[0,0,0]
	v_mfma_scale_f32_16x16x128_f8f6f4 v[138:141], v[24:31], v[198:205], v[138:141], v220, v221 op_sel_hi:[0,0,0]
	v_mfma_scale_f32_16x16x128_f8f6f4 v[134:137], v[16:23], v[206:213], v[134:137], v220, v221 op_sel_hi:[0,0,0]
	v_mfma_scale_f32_16x16x128_f8f6f4 v[130:133], v[24:31], v[206:213], v[130:133], v220, v221 op_sel_hi:[0,0,0]
	s_setprio 0
	s_setprio 1
	v_mfma_scale_f32_16x16x128_f8f6f4 v[126:129], v[0:7], v[176:183], v[126:129], v220, v221 op_sel_hi:[0,0,0]
	v_mfma_scale_f32_16x16x128_f8f6f4 v[122:125], v[8:15], v[176:183], v[122:125], v220, v221 op_sel_hi:[0,0,0]
	v_mfma_scale_f32_16x16x128_f8f6f4 v[118:121], v[0:7], v[184:191], v[118:121], v220, v221 op_sel_hi:[0,0,0]
	v_mfma_scale_f32_16x16x128_f8f6f4 v[114:117], v[8:15], v[184:191], v[114:117], v220, v221 op_sel_hi:[0,0,0]
	v_mfma_scale_f32_16x16x128_f8f6f4 v[110:113], v[0:7], v[198:205], v[110:113], v220, v221 op_sel_hi:[0,0,0]
	v_mfma_scale_f32_16x16x128_f8f6f4 v[106:109], v[8:15], v[198:205], v[106:109], v220, v221 op_sel_hi:[0,0,0]
	v_mfma_scale_f32_16x16x128_f8f6f4 v[102:105], v[0:7], v[206:213], v[102:105], v220, v221 op_sel_hi:[0,0,0]
	v_mfma_scale_f32_16x16x128_f8f6f4 v[98:101], v[8:15], v[206:213], v[98:101], v220, v221 op_sel_hi:[0,0,0]
	s_setprio 2
	s_barrier
	v_mov_b32_e32 v173, v33
	s_add_i32 s36, s36, s49
	v_lshl_add_u64 v[170:171], s[26:27], 0, v[172:173]
	s_mov_b32 m0, s36
	ds_read_b128 v[176:179], v174 offset:16384
	ds_read_b128 v[180:183], v174 offset:17408
	ds_read_b128 v[184:187], v174 offset:18432
	ds_read_b128 v[188:191], v174 offset:19456
	ds_read_b128 v[198:201], v174 offset:20480
	ds_read_b128 v[202:205], v174 offset:21504
	ds_read_b128 v[206:209], v174 offset:22528
	ds_read_b128 v[210:213], v174 offset:23552
	global_load_lds_dwordx4 v172, s[26:27]
	v_lshl_add_u64 v[172:173], v[170:171], 0, s[38:39]
	s_add_i32 m0, s36, 0x2000
	s_add_i32 s26, s68, s49
	global_load_lds_dwordx4 v[172:173], off
	v_lshl_add_u64 v[172:173], v[170:171], 0, s[60:61]
	s_mov_b32 m0, s26
	s_nop 0
	global_load_lds_dwordx4 v[172:173], off
	v_lshl_add_u64 v[172:173], v[170:171], 0, s[0:1]
	s_add_i32 m0, s26, 0x2000
	s_nop 0
	global_load_lds_dwordx4 v[172:173], off
	v_lshl_add_u64 v[172:173], s[24:25], 0, v[32:33]
	s_mov_b32 m0, s31
	v_lshl_add_u64 v[192:193], v[172:173], 0, s[38:39]
	global_load_lds_dwordx4 v[172:173], off
	s_mov_b32 m0, s34
	s_nop 0
	global_load_lds_dwordx4 v[192:193], off
	s_waitcnt vmcnt(8)
	s_waitcnt lgkmcnt(0)
	s_barrier
	s_setprio 1
	s_waitcnt lgkmcnt(0)
	v_mfma_scale_f32_16x16x128_f8f6f4 v[94:97], v[16:23], v[176:183], v[94:97], v220, v221 op_sel_hi:[0,0,0]
	v_mfma_scale_f32_16x16x128_f8f6f4 v[90:93], v[24:31], v[176:183], v[90:93], v220, v221 op_sel_hi:[0,0,0]
	v_mfma_scale_f32_16x16x128_f8f6f4 v[86:89], v[16:23], v[184:191], v[86:89], v220, v221 op_sel_hi:[0,0,0]
	v_mfma_scale_f32_16x16x128_f8f6f4 v[82:85], v[24:31], v[184:191], v[82:85], v220, v221 op_sel_hi:[0,0,0]
	v_mfma_scale_f32_16x16x128_f8f6f4 v[78:81], v[16:23], v[198:205], v[78:81], v220, v221 op_sel_hi:[0,0,0]
	v_mfma_scale_f32_16x16x128_f8f6f4 v[74:77], v[24:31], v[198:205], v[74:77], v220, v221 op_sel_hi:[0,0,0]
	v_mfma_scale_f32_16x16x128_f8f6f4 v[70:73], v[16:23], v[206:213], v[70:73], v220, v221 op_sel_hi:[0,0,0]
	v_mfma_scale_f32_16x16x128_f8f6f4 v[66:69], v[24:31], v[206:213], v[66:69], v220, v221 op_sel_hi:[0,0,0]
	s_setprio 0
	s_setprio 1
	v_mfma_scale_f32_16x16x128_f8f6f4 v[62:65], v[0:7], v[176:183], v[62:65], v220, v221 op_sel_hi:[0,0,0]
	v_mfma_scale_f32_16x16x128_f8f6f4 v[58:61], v[8:15], v[176:183], v[58:61], v220, v221 op_sel_hi:[0,0,0]
	v_mfma_scale_f32_16x16x128_f8f6f4 v[54:57], v[0:7], v[184:191], v[54:57], v220, v221 op_sel_hi:[0,0,0]
	v_mfma_scale_f32_16x16x128_f8f6f4 v[50:53], v[8:15], v[184:191], v[50:53], v220, v221 op_sel_hi:[0,0,0]
	v_mfma_scale_f32_16x16x128_f8f6f4 v[46:49], v[0:7], v[198:205], v[46:49], v220, v221 op_sel_hi:[0,0,0]
	v_mfma_scale_f32_16x16x128_f8f6f4 v[42:45], v[8:15], v[198:205], v[42:45], v220, v221 op_sel_hi:[0,0,0]
	v_mfma_scale_f32_16x16x128_f8f6f4 v[38:41], v[0:7], v[206:213], v[38:41], v220, v221 op_sel_hi:[0,0,0]
	v_mfma_scale_f32_16x16x128_f8f6f4 v[34:37], v[8:15], v[206:213], v[34:37], v220, v221 op_sel_hi:[0,0,0]
	s_setprio 2
	s_barrier
; #define PG8_STAGE(bufoff, gbase, voff, h64) do { \
;         __builtin_amdgcn_global_load_lds((const unsigned*)((const char*)(gbase) + (voff)), (LAS unsigned*)(lds + (bufoff) + ldsw), 16, 0, 0); \
;         __builtin_amdgcn_global_load_lds((const unsigned*)((const char*)(gbase) + (h64) + (voff)), (LAS unsigned*)(lds + (bufoff) + ldsw + 8192), 16, 0, 0); } while (0)
; #define PG8_LDA(dst, b, h) do { _Pragma("unroll") for (int m = 0; m < 4; ++m) { dst[m].lo = *(const LAS f16x8*)(lds + PG8_SA(b, h) + aoff + m * 2048); dst[m].hi = *(const LAS f16x8*)(lds + PG8_SA(b, h) + aoff + m * 2048 + 1024); } } while (0)
; #define PG8_LDB(dst, b, h) do { _Pragma("unroll") for (int n = 0; n < 2; ++n) { dst[n].lo = *(const LAS f16x8*)(lds + PG8_SB(b, h) + boff + n * 2048); dst[n].hi = *(const LAS f16x8*)(lds + PG8_SB(b, h) + boff + n * 2048 + 1024); } } while (0)
; #define PG8_WAIT_V(n) asm volatile("s_waitcnt vmcnt(" #n ")" ::: "memory")
; #define PG8_WAIT_L(n) asm volatile("s_waitcnt lgkmcnt(" #n ")" ::: "memory")
; #define PG8_BAR __builtin_amdgcn_s_barrier()
; #define PG8_SCHED __builtin_amdgcn_sched_barrier(0)
; template <bool F8 = false, class Sched, class Epi>
; __device__ __forceinline__ void gemm_phase(LAS unsigned char* lds, const Sched& S, const Epi& E) {
;     ...
;             PG8_LDB(B0, 1, 0); PG8_LDB(B1, 1, 1); PG8_SCHED; PG8_LDA(At, 1, 0); PG8_STAGE(PG8_SA(0, 1), a2 + hs2, vA2, h2);
;             PG8_WAIT_V(8); PG8_WAIT_L(0); PG8_BAR; PG8_MMA(0, 0, At, B0); PG8_MMA(0, 1, At, B1); PG8_BAR; PG8_SCHED;
;             PG8_LDA(At, 1, 1); PG8_STAGE(PG8_SB(1, 0), b3, vB2, h2); PG8_STAGE(PG8_SB(1, 1), b3 + bhs2, vB2, h2); PG8_STAGE(PG8_SA(1, 0), a3, vA2, h2);
;             PG8_WAIT_V(8); PG8_WAIT_L(0); PG8_BAR; PG8_MMA(1, 0, At, B0); PG8_MMA(1, 1, At, B1); PG8_BAR; PG8_SCHED;
;         }
;         if (wr == 0) PG8_BAR;
	s_add_i32 s24, 0, 0x18000
	s_add_i32 s25, 0, 0x1c000
	v_add_u32_e32 v12, s24, v163
	v_add_u32_e32 v28, s25, v163
	ds_read_b128 v[0:3], v12
	ds_read_b128 v[4:7], v12 offset:1024
	ds_read_b128 v[8:11], v12 offset:2048
	ds_read_b128 v[12:15], v12 offset:3072
	ds_read_b128 v[16:19], v28
	ds_read_b128 v[20:23], v28 offset:1024
	ds_read_b128 v[24:27], v28 offset:2048
	ds_read_b128 v[28:31], v28 offset:3072
	s_mov_b32 m0, s35
	v_lshl_add_u64 v[192:193], v[172:173], 0, s[60:61]
	ds_read_b128 v[176:179], v174 offset:32768
	ds_read_b128 v[180:183], v174 offset:33792
	ds_read_b128 v[184:187], v174 offset:34816
	ds_read_b128 v[188:191], v174 offset:35840
	ds_read_b128 v[198:201], v174 offset:36864
	ds_read_b128 v[202:205], v174 offset:37888
	ds_read_b128 v[206:209], v174 offset:38912
	ds_read_b128 v[210:213], v174 offset:39936
	global_load_lds_dwordx4 v[192:193], off
	v_lshl_add_u64 v[192:193], v[172:173], 0, s[0:1]
	s_mov_b32 m0, s37
	s_nop 0
	global_load_lds_dwordx4 v[192:193], off
	s_waitcnt vmcnt(8)
	s_waitcnt lgkmcnt(0)
	s_barrier
	s_setprio 1
	s_waitcnt lgkmcnt(0)
	v_mfma_scale_f32_16x16x128_f8f6f4 v[158:161], v[0:7], v[176:183], v[158:161], v220, v221 op_sel_hi:[0,0,0]
	v_mfma_scale_f32_16x16x128_f8f6f4 v[154:157], v[8:15], v[176:183], v[154:157], v220, v221 op_sel_hi:[0,0,0]
	v_mfma_scale_f32_16x16x128_f8f6f4 v[150:153], v[0:7], v[184:191], v[150:153], v220, v221 op_sel_hi:[0,0,0]
	v_mfma_scale_f32_16x16x128_f8f6f4 v[146:149], v[8:15], v[184:191], v[146:149], v220, v221 op_sel_hi:[0,0,0]
	v_mfma_scale_f32_16x16x128_f8f6f4 v[142:145], v[0:7], v[198:205], v[142:145], v220, v221 op_sel_hi:[0,0,0]
	v_mfma_scale_f32_16x16x128_f8f6f4 v[138:141], v[8:15], v[198:205], v[138:141], v220, v221 op_sel_hi:[0,0,0]
	v_mfma_scale_f32_16x16x128_f8f6f4 v[134:137], v[0:7], v[206:213], v[134:137], v220, v221 op_sel_hi:[0,0,0]
	v_mfma_scale_f32_16x16x128_f8f6f4 v[130:133], v[8:15], v[206:213], v[130:133], v220, v221 op_sel_hi:[0,0,0]
	s_setprio 0
	s_setprio 1
	v_mfma_scale_f32_16x16x128_f8f6f4 v[126:129], v[16:23], v[176:183], v[126:129], v220, v221 op_sel_hi:[0,0,0]
	v_mfma_scale_f32_16x16x128_f8f6f4 v[122:125], v[24:31], v[176:183], v[122:125], v220, v221 op_sel_hi:[0,0,0]
	v_mfma_scale_f32_16x16x128_f8f6f4 v[118:121], v[16:23], v[184:191], v[118:121], v220, v221 op_sel_hi:[0,0,0]
	v_mfma_scale_f32_16x16x128_f8f6f4 v[114:117], v[24:31], v[184:191], v[114:117], v220, v221 op_sel_hi:[0,0,0]
	v_mfma_scale_f32_16x16x128_f8f6f4 v[110:113], v[16:23], v[198:205], v[110:113], v220, v221 op_sel_hi:[0,0,0]
	v_mfma_scale_f32_16x16x128_f8f6f4 v[106:109], v[24:31], v[198:205], v[106:109], v220, v221 op_sel_hi:[0,0,0]
	v_mfma_scale_f32_16x16x128_f8f6f4 v[102:105], v[16:23], v[206:213], v[102:105], v220, v221 op_sel_hi:[0,0,0]
	v_mfma_scale_f32_16x16x128_f8f6f4 v[98:101], v[24:31], v[206:213], v[98:101], v220, v221 op_sel_hi:[0,0,0]
	s_setprio 2
	s_barrier
	s_add_i32 s24, s24, s49
	v_lshl_add_u64 v[192:193], v[170:171], 0, s[40:41]
	s_mov_b32 m0, s24
	ds_read_b128 v[176:179], v174 offset:49152
	ds_read_b128 v[180:183], v174 offset:50176
	ds_read_b128 v[184:187], v174 offset:51200
	ds_read_b128 v[188:191], v174 offset:52224
	ds_read_b128 v[198:201], v174 offset:53248
	ds_read_b128 v[202:205], v174 offset:54272
	ds_read_b128 v[206:209], v174 offset:55296
	ds_read_b128 v[210:213], v174 offset:56320
	global_load_lds_dwordx4 v[192:193], off
	v_lshl_add_u64 v[192:193], v[170:171], 0, s[56:57]
	s_add_i32 m0, s24, 0x2000
	s_add_i32 s24, s25, s49
	global_load_lds_dwordx4 v[192:193], off
	v_lshl_add_u64 v[192:193], v[170:171], 0, s[58:59]
	s_mov_b32 m0, s24
	v_lshl_add_u64 v[170:171], v[170:171], 0, s[76:77]
	global_load_lds_dwordx4 v[192:193], off
	s_add_i32 m0, s24, 0x2000
	s_nop 0
	global_load_lds_dwordx4 v[170:171], off
	v_lshl_add_u64 v[170:171], v[172:173], 0, s[40:41]
	s_mov_b32 m0, s42
	s_nop 0
	global_load_lds_dwordx4 v[170:171], off
	v_lshl_add_u64 v[170:171], v[172:173], 0, s[56:57]
	s_mov_b32 m0, s43
	s_nop 0
	global_load_lds_dwordx4 v[170:171], off
	s_waitcnt vmcnt(8)
	s_waitcnt lgkmcnt(0)
	s_barrier
	s_setprio 1
	s_waitcnt lgkmcnt(0)
	v_mfma_scale_f32_16x16x128_f8f6f4 v[94:97], v[0:7], v[176:183], v[94:97], v220, v221 op_sel_hi:[0,0,0]
	v_mfma_scale_f32_16x16x128_f8f6f4 v[90:93], v[8:15], v[176:183], v[90:93], v220, v221 op_sel_hi:[0,0,0]
	v_mfma_scale_f32_16x16x128_f8f6f4 v[86:89], v[0:7], v[184:191], v[86:89], v220, v221 op_sel_hi:[0,0,0]
	v_mfma_scale_f32_16x16x128_f8f6f4 v[82:85], v[8:15], v[184:191], v[82:85], v220, v221 op_sel_hi:[0,0,0]
	v_mfma_scale_f32_16x16x128_f8f6f4 v[78:81], v[0:7], v[198:205], v[78:81], v220, v221 op_sel_hi:[0,0,0]
	v_mfma_scale_f32_16x16x128_f8f6f4 v[74:77], v[8:15], v[198:205], v[74:77], v220, v221 op_sel_hi:[0,0,0]
	v_mfma_scale_f32_16x16x128_f8f6f4 v[70:73], v[0:7], v[206:213], v[70:73], v220, v221 op_sel_hi:[0,0,0]
	v_mfma_scale_f32_16x16x128_f8f6f4 v[66:69], v[8:15], v[206:213], v[66:69], v220, v221 op_sel_hi:[0,0,0]
	s_setprio 0
	s_setprio 1
	v_mfma_scale_f32_16x16x128_f8f6f4 v[62:65], v[16:23], v[176:183], v[62:65], v220, v221 op_sel_hi:[0,0,0]
	v_mfma_scale_f32_16x16x128_f8f6f4 v[58:61], v[24:31], v[176:183], v[58:61], v220, v221 op_sel_hi:[0,0,0]
	v_mfma_scale_f32_16x16x128_f8f6f4 v[54:57], v[16:23], v[184:191], v[54:57], v220, v221 op_sel_hi:[0,0,0]
	v_mfma_scale_f32_16x16x128_f8f6f4 v[50:53], v[24:31], v[184:191], v[50:53], v220, v221 op_sel_hi:[0,0,0]
	v_mfma_scale_f32_16x16x128_f8f6f4 v[46:49], v[16:23], v[198:205], v[46:49], v220, v221 op_sel_hi:[0,0,0]
	v_mfma_scale_f32_16x16x128_f8f6f4 v[42:45], v[24:31], v[198:205], v[42:45], v220, v221 op_sel_hi:[0,0,0]
	v_mfma_scale_f32_16x16x128_f8f6f4 v[38:41], v[16:23], v[206:213], v[38:41], v220, v221 op_sel_hi:[0,0,0]
	v_mfma_scale_f32_16x16x128_f8f6f4 v[34:37], v[24:31], v[206:213], v[34:37], v220, v221 op_sel_hi:[0,0,0]
	s_setprio 2
	s_barrier
	s_add_i32 s81, s81, 2
	s_add_u32 s8, s8, 0x100
	s_addc_u32 s9, s9, 0
	s_cmp_gt_u32 s81, 5
	s_cbranch_scc0 .LBB0_73
	v_readlane_b32 s8, v251, 12
	v_readlane_b32 s9, v251, 13
	s_and_b64 vcc, exec, s[8:9]
	s_cbranch_vccz .LBB0_76
	s_barrier

; #define PG8_STAGE(bufoff, gbase, voff, h64) do { \
;         __builtin_amdgcn_global_load_lds((const unsigned*)((const char*)(gbase) + (voff)), (LAS unsigned*)(lds + (bufoff) + ldsw), 16, 0, 0); \
;         __builtin_amdgcn_global_load_lds((const unsigned*)((const char*)(gbase) + (h64) + (voff)), (LAS unsigned*)(lds + (bufoff) + ldsw + 8192), 16, 0, 0); } while (0)
; #define PG8_LDA(dst, b, h) do { _Pragma("unroll") for (int m = 0; m < 4; ++m) { dst[m].lo = *(const LAS f16x8*)(lds + PG8_SA(b, h) + aoff + m * 2048); dst[m].hi = *(const LAS f16x8*)(lds + PG8_SA(b, h) + aoff + m * 2048 + 1024); } } while (0)
; #define PG8_LDB(dst, b, h) do { _Pragma("unroll") for (int n = 0; n < 2; ++n) { dst[n].lo = *(const LAS f16x8*)(lds + PG8_SB(b, h) + boff + n * 2048); dst[n].hi = *(const LAS f16x8*)(lds + PG8_SB(b, h) + boff + n * 2048 + 1024); } } while (0)
; #define PG8_WAIT_V(n) asm volatile("s_waitcnt vmcnt(" #n ")" ::: "memory")
; #define PG8_WAIT_L(n) asm volatile("s_waitcnt lgkmcnt(" #n ")" ::: "memory")
; #define PG8_BAR __builtin_amdgcn_s_barrier()
; #define PG8_SCHED __builtin_amdgcn_sched_barrier(0)
; template <bool F8 = false, class Sched, class Epi>
; __device__ __forceinline__ void gemm_phase(LAS unsigned char* lds, const Sched& S, const Epi& E) {
;     ...
;             PG8_LDB(B0, 0, 0); PG8_LDB(B1, 0, 1); PG8_SCHED; PG8_LDA(At, 0, 0); PG8_STAGE(PG8_SA(1, 1), a1 + chs, cvA, ch64);
;             PG8_WAIT_V(8); PG8_WAIT_L(0); PG8_BAR; PG8_MMA(0, 0, At, B0); PG8_MMA(0, 1, At, B1); PG8_BAR; PG8_SCHED;
;             PG8_LDA(At, 0, 1); PG8_STAGE(PG8_SB(0, 0), b2, vB2, h2); PG8_STAGE(PG8_SB(0, 1), b2 + bhs2, vB2, h2); PG8_STAGE(PG8_SA(0, 0), a2, vA2, h2);
;             PG8_WAIT_V(8); PG8_WAIT_L(0); PG8_BAR; PG8_MMA(1, 0, At, B0); PG8_MMA(1, 1, At, B1); PG8_BAR; PG8_SCHED;
.LBB0_214:
	s_add_i32 s79, s79, 2
	s_add_u32 vcc_lo, s14, s10
	s_addc_u32 vcc_hi, s15, s11
	s_add_u32 vcc_lo, vcc_lo, 0x100
	s_addc_u32 vcc_hi, vcc_hi, 0
	s_and_b64 s[86:87], exec, s[86:87]
	s_cselect_b32 vcc_hi, s29, vcc_hi
	s_cselect_b32 vcc_lo, s96, vcc_lo
	s_add_i32 s86, 0, 0x10000
	s_add_i32 s45, 0, 0x14000
	v_add_u32_e32 v150, s86, v187
	v_add_u32_e32 v166, s45, v187
	ds_read_b128 v[138:141], v150
	ds_read_b128 v[142:145], v150 offset:1024
	ds_read_b128 v[146:149], v150 offset:2048
	ds_read_b128 v[150:153], v150 offset:3072
	ds_read_b128 v[154:157], v166
	ds_read_b128 v[158:161], v166 offset:1024
	ds_read_b128 v[162:165], v166 offset:2048
	ds_read_b128 v[166:169], v166 offset:3072
	v_lshl_add_u64 v[182:183], v[132:133], 0, s[10:11]
	s_add_i32 m0, s71, 0xc000
	ds_read_b128 v[170:173], v202
	ds_read_b128 v[174:177], v202 offset:1024
	ds_read_b128 v[178:181], v202 offset:2048
	ds_read_b128 v[190:193], v202 offset:3072
	ds_read_b128 v[198:201], v202 offset:4096
	ds_read_b128 v[204:207], v202 offset:5120
	ds_read_b128 v[208:211], v202 offset:6144
	ds_read_b128 v[212:215], v202 offset:7168
	global_load_lds_dwordx4 v[182:183], off
	v_lshl_add_u64 v[182:183], v[134:135], 0, s[10:11]
	s_add_i32 m0, s71, 0xe000
	s_nop 0
	global_load_lds_dwordx4 v[182:183], off
	s_waitcnt vmcnt(8)
	s_waitcnt lgkmcnt(0)
	s_barrier
	s_setprio 1
	s_waitcnt lgkmcnt(0)
	v_mfma_f32_16x16x32_f16 v[128:131], v[138:141], v[170:173], v[128:131]
	v_mfma_f32_16x16x32_f16 v[124:127], v[146:149], v[170:173], v[124:127]
	v_mfma_f32_16x16x32_f16 v[112:115], v[138:141], v[178:181], v[112:115]
	v_mfma_f32_16x16x32_f16 v[108:111], v[146:149], v[178:181], v[108:111]
	v_mfma_f32_16x16x32_f16 v[96:99], v[138:141], v[198:201], v[96:99]
	v_mfma_f32_16x16x32_f16 v[92:95], v[146:149], v[198:201], v[92:95]
	v_mfma_f32_16x16x32_f16 v[80:83], v[138:141], v[208:211], v[80:83]
	v_mfma_f32_16x16x32_f16 v[76:79], v[146:149], v[208:211], v[76:79]
	v_mfma_f32_16x16x32_f16 v[128:131], v[142:145], v[174:177], v[128:131]
	v_mfma_f32_16x16x32_f16 v[124:127], v[150:153], v[174:177], v[124:127]
	v_mfma_f32_16x16x32_f16 v[112:115], v[142:145], v[190:193], v[112:115]
	v_mfma_f32_16x16x32_f16 v[108:111], v[150:153], v[190:193], v[108:111]
	v_mfma_f32_16x16x32_f16 v[96:99], v[142:145], v[204:207], v[96:99]
	v_mfma_f32_16x16x32_f16 v[92:95], v[150:153], v[204:207], v[92:95]
	v_mfma_f32_16x16x32_f16 v[80:83], v[142:145], v[212:215], v[80:83]
	v_mfma_f32_16x16x32_f16 v[76:79], v[150:153], v[212:215], v[76:79]
	s_setprio 0
	s_setprio 1
	v_mfma_f32_16x16x32_f16 v[120:123], v[154:157], v[170:173], v[120:123]
	v_mfma_f32_16x16x32_f16 v[116:119], v[162:165], v[170:173], v[116:119]
	v_mfma_f32_16x16x32_f16 v[104:107], v[154:157], v[178:181], v[104:107]
	v_mfma_f32_16x16x32_f16 v[100:103], v[162:165], v[178:181], v[100:103]
	v_mfma_f32_16x16x32_f16 v[88:91], v[154:157], v[198:201], v[88:91]
	v_mfma_f32_16x16x32_f16 v[84:87], v[162:165], v[198:201], v[84:87]
	v_mfma_f32_16x16x32_f16 v[72:75], v[154:157], v[208:211], v[72:75]
	v_mfma_f32_16x16x32_f16 v[68:71], v[162:165], v[208:211], v[68:71]
	v_mfma_f32_16x16x32_f16 v[120:123], v[158:161], v[174:177], v[120:123]
	v_mfma_f32_16x16x32_f16 v[116:119], v[166:169], v[174:177], v[116:119]
	v_mfma_f32_16x16x32_f16 v[104:107], v[158:161], v[190:193], v[104:107]
	v_mfma_f32_16x16x32_f16 v[100:103], v[166:169], v[190:193], v[100:103]
	v_mfma_f32_16x16x32_f16 v[88:91], v[158:161], v[204:207], v[88:91]
	v_mfma_f32_16x16x32_f16 v[84:87], v[166:169], v[204:207], v[84:87]
	v_mfma_f32_16x16x32_f16 v[72:75], v[158:161], v[212:215], v[72:75]
	v_mfma_f32_16x16x32_f16 v[68:71], v[166:169], v[212:215], v[68:71]
	s_setprio 2
	s_barrier
	s_add_i32 s65, s86, s49
	s_mov_b32 m0, s65
	s_add_u32 s86, s6, s12
	ds_read_b128 v[170:173], v202 offset:16384
	ds_read_b128 v[174:177], v202 offset:17408
	ds_read_b128 v[178:181], v202 offset:18432
	ds_read_b128 v[190:193], v202 offset:19456
	ds_read_b128 v[198:201], v202 offset:20480
	ds_read_b128 v[204:207], v202 offset:21504
	ds_read_b128 v[208:211], v202 offset:22528
	ds_read_b128 v[212:215], v202 offset:23552
	global_load_lds_dwordx4 v32, s[6:7]
	s_addc_u32 s87, s7, s13
	s_add_i32 m0, s65, 0x2000
	v_lshl_add_u64 v[182:183], s[6:7], 0, v[32:33]
	s_add_u32 s6, s6, s8
	s_addc_u32 s7, s7, s9
	s_add_i32 s8, s45, s49
	global_load_lds_dwordx4 v32, s[86:87]
	s_mov_b32 m0, s8
	v_lshl_add_u64 v[216:217], s[6:7], 0, v[32:33]
	global_load_lds_dwordx4 v32, s[6:7]
	s_add_u32 s6, s6, s12
	s_addc_u32 s7, s7, s13
	s_add_i32 m0, s8, 0x2000
	v_lshl_add_u64 v[234:235], s[6:7], 0, v[32:33]
	global_load_lds_dwordx4 v32, s[6:7]
	s_add_u32 s6, vcc_lo, s12
	v_lshl_add_u64 v[236:237], vcc, 0, v[136:137]
	s_mov_b32 m0, s71
	s_addc_u32 s7, vcc_hi, s13
	global_load_lds_dwordx4 v[236:237], off
	v_lshl_add_u64 v[238:239], s[6:7], 0, v[136:137]
	s_mov_b32 m0, s82
	v_lshl_add_u64 v[194:195], s[86:87], 0, v[32:33]
	global_load_lds_dwordx4 v[238:239], off
	s_waitcnt vmcnt(8)
	s_waitcnt lgkmcnt(0)
	s_barrier
; #define PG8_STAGE(bufoff, gbase, voff, h64) do { \
;         __builtin_amdgcn_global_load_lds((const unsigned*)((const char*)(gbase) + (voff)), (LAS unsigned*)(lds + (bufoff) + ldsw), 16, 0, 0); \
;         __builtin_amdgcn_global_load_lds((const unsigned*)((const char*)(gbase) + (h64) + (voff)), (LAS unsigned*)(lds + (bufoff) + ldsw + 8192), 16, 0, 0); } while (0)
; #define PG8_LDA(dst, b, h) do { _Pragma("unroll") for (int m = 0; m < 4; ++m) { dst[m].lo = *(const LAS f16x8*)(lds + PG8_SA(b, h) + aoff + m * 2048); dst[m].hi = *(const LAS f16x8*)(lds + PG8_SA(b, h) + aoff + m * 2048 + 1024); } } while (0)
; #define PG8_LDB(dst, b, h) do { _Pragma("unroll") for (int n = 0; n < 2; ++n) { dst[n].lo = *(const LAS f16x8*)(lds + PG8_SB(b, h) + boff + n * 2048); dst[n].hi = *(const LAS f16x8*)(lds + PG8_SB(b, h) + boff + n * 2048 + 1024); } } while (0)
; #define PG8_WAIT_V(n) asm volatile("s_waitcnt vmcnt(" #n ")" ::: "memory")
; #define PG8_WAIT_L(n) asm volatile("s_waitcnt lgkmcnt(" #n ")" ::: "memory")
; #define PG8_BAR __builtin_amdgcn_s_barrier()
; #define PG8_SCHED __builtin_amdgcn_sched_barrier(0)
; template <bool F8 = false, class Sched, class Epi>
; __device__ __forceinline__ void gemm_phase(LAS unsigned char* lds, const Sched& S, const Epi& E) {
;     ...
;             PG8_WAIT_V(8); PG8_WAIT_L(0); PG8_BAR; PG8_MMA(1, 0, At, B0); PG8_MMA(1, 1, At, B1); PG8_BAR; PG8_SCHED;
;             PG8_LDB(B0, 1, 0); PG8_LDB(B1, 1, 1); PG8_SCHED; PG8_LDA(At, 1, 0); PG8_STAGE(PG8_SA(0, 1), a2 + hs2, vA2, h2);
;             PG8_WAIT_V(8); PG8_WAIT_L(0); PG8_BAR; PG8_MMA(0, 0, At, B0); PG8_MMA(0, 1, At, B1); PG8_BAR; PG8_SCHED;
	s_setprio 1
	s_waitcnt lgkmcnt(0)
	v_mfma_f32_16x16x32_f16 v[64:67], v[138:141], v[170:173], v[64:67]
	v_mfma_f32_16x16x32_f16 v[60:63], v[146:149], v[170:173], v[60:63]
	v_mfma_f32_16x16x32_f16 v[48:51], v[138:141], v[178:181], v[48:51]
	v_mfma_f32_16x16x32_f16 v[44:47], v[146:149], v[178:181], v[44:47]
	v_mfma_f32_16x16x32_f16 v[28:31], v[138:141], v[198:201], v[28:31]
	v_mfma_f32_16x16x32_f16 v[24:27], v[146:149], v[198:201], v[24:27]
	v_mfma_f32_16x16x32_f16 v[12:15], v[138:141], v[208:211], v[12:15]
	v_mfma_f32_16x16x32_f16 v[8:11], v[146:149], v[208:211], v[8:11]
	v_mfma_f32_16x16x32_f16 v[64:67], v[142:145], v[174:177], v[64:67]
	v_mfma_f32_16x16x32_f16 v[60:63], v[150:153], v[174:177], v[60:63]
	v_mfma_f32_16x16x32_f16 v[48:51], v[142:145], v[190:193], v[48:51]
	v_mfma_f32_16x16x32_f16 v[44:47], v[150:153], v[190:193], v[44:47]
	v_mfma_f32_16x16x32_f16 v[28:31], v[142:145], v[204:207], v[28:31]
	v_mfma_f32_16x16x32_f16 v[24:27], v[150:153], v[204:207], v[24:27]
	v_mfma_f32_16x16x32_f16 v[12:15], v[142:145], v[212:215], v[12:15]
	v_mfma_f32_16x16x32_f16 v[8:11], v[150:153], v[212:215], v[8:11]
	s_setprio 0
	s_setprio 1
	v_mfma_f32_16x16x32_f16 v[56:59], v[154:157], v[170:173], v[56:59]
	v_mfma_f32_16x16x32_f16 v[52:55], v[162:165], v[170:173], v[52:55]
	v_mfma_f32_16x16x32_f16 v[40:43], v[154:157], v[178:181], v[40:43]
	v_mfma_f32_16x16x32_f16 v[36:39], v[162:165], v[178:181], v[36:39]
	v_mfma_f32_16x16x32_f16 v[20:23], v[154:157], v[198:201], v[20:23]
	v_mfma_f32_16x16x32_f16 v[16:19], v[162:165], v[198:201], v[16:19]
	v_mfma_f32_16x16x32_f16 v[4:7], v[154:157], v[208:211], v[4:7]
	v_mfma_f32_16x16x32_f16 v[0:3], v[162:165], v[208:211], v[0:3]
	v_mfma_f32_16x16x32_f16 v[56:59], v[158:161], v[174:177], v[56:59]
	v_mfma_f32_16x16x32_f16 v[52:55], v[166:169], v[174:177], v[52:55]
	v_mfma_f32_16x16x32_f16 v[40:43], v[158:161], v[190:193], v[40:43]
	v_mfma_f32_16x16x32_f16 v[36:39], v[166:169], v[190:193], v[36:39]
	v_mfma_f32_16x16x32_f16 v[20:23], v[158:161], v[204:207], v[20:23]
	v_mfma_f32_16x16x32_f16 v[16:19], v[166:169], v[204:207], v[16:19]
	v_mfma_f32_16x16x32_f16 v[4:7], v[158:161], v[212:215], v[4:7]
	v_mfma_f32_16x16x32_f16 v[0:3], v[166:169], v[212:215], v[0:3]
	s_setprio 2
	s_barrier
	s_add_i32 s8, 0, 0x18000
	v_add_u32_e32 v32, s8, v187
	s_add_i32 s9, 0, 0x1c000
	ds_read_b128 v[138:141], v32
	ds_read_b128 v[142:145], v32 offset:1024
	ds_read_b128 v[146:149], v32 offset:2048
	ds_read_b128 v[150:153], v32 offset:3072
	v_add_u32_e32 v32, s9, v187
	ds_read_b128 v[154:157], v32
	ds_read_b128 v[158:161], v32 offset:1024
	ds_read_b128 v[162:165], v32 offset:2048
	ds_read_b128 v[166:169], v32 offset:3072
	s_add_u32 s6, vcc_lo, s84
	s_addc_u32 s7, vcc_hi, s85
	v_lshl_add_u64 v[240:241], s[6:7], 0, v[136:137]
	s_add_u32 s6, s6, s12
	s_mov_b32 m0, s83
	s_addc_u32 s7, s7, s13
	ds_read_b128 v[170:173], v202 offset:32768
	ds_read_b128 v[174:177], v202 offset:33792
	ds_read_b128 v[178:181], v202 offset:34816
	ds_read_b128 v[190:193], v202 offset:35840
	ds_read_b128 v[198:201], v202 offset:36864
	ds_read_b128 v[204:207], v202 offset:37888
	ds_read_b128 v[208:211], v202 offset:38912
	ds_read_b128 v[212:215], v202 offset:39936
	global_load_lds_dwordx4 v[240:241], off
	v_lshl_add_u64 v[136:137], s[6:7], 0, v[136:137]
	s_mov_b32 m0, s44
	s_nop 0
	global_load_lds_dwordx4 v[136:137], off
	s_waitcnt vmcnt(8)
	s_waitcnt lgkmcnt(0)
	s_barrier
	s_setprio 1
	s_waitcnt lgkmcnt(0)
	v_mfma_f32_16x16x32_f16 v[128:131], v[138:141], v[170:173], v[128:131]
	v_mfma_f32_16x16x32_f16 v[124:127], v[146:149], v[170:173], v[124:127]
	v_mfma_f32_16x16x32_f16 v[112:115], v[138:141], v[178:181], v[112:115]
	v_mfma_f32_16x16x32_f16 v[108:111], v[146:149], v[178:181], v[108:111]
	v_mfma_f32_16x16x32_f16 v[96:99], v[138:141], v[198:201], v[96:99]
	v_mfma_f32_16x16x32_f16 v[92:95], v[146:149], v[198:201], v[92:95]
	v_mfma_f32_16x16x32_f16 v[80:83], v[138:141], v[208:211], v[80:83]
	v_mfma_f32_16x16x32_f16 v[76:79], v[146:149], v[208:211], v[76:79]
	v_mfma_f32_16x16x32_f16 v[128:131], v[142:145], v[174:177], v[128:131]
	v_mfma_f32_16x16x32_f16 v[124:127], v[150:153], v[174:177], v[124:127]
	v_mfma_f32_16x16x32_f16 v[112:115], v[142:145], v[190:193], v[112:115]
	v_mfma_f32_16x16x32_f16 v[108:111], v[150:153], v[190:193], v[108:111]
	v_mfma_f32_16x16x32_f16 v[96:99], v[142:145], v[204:207], v[96:99]
	v_mfma_f32_16x16x32_f16 v[92:95], v[150:153], v[204:207], v[92:95]
	v_mfma_f32_16x16x32_f16 v[80:83], v[142:145], v[212:215], v[80:83]
	v_mfma_f32_16x16x32_f16 v[76:79], v[150:153], v[212:215], v[76:79]
	s_setprio 0
	s_setprio 1
	v_mfma_f32_16x16x32_f16 v[120:123], v[154:157], v[170:173], v[120:123]
	v_mfma_f32_16x16x32_f16 v[116:119], v[162:165], v[170:173], v[116:119]
	v_mfma_f32_16x16x32_f16 v[104:107], v[154:157], v[178:181], v[104:107]
	v_mfma_f32_16x16x32_f16 v[100:103], v[162:165], v[178:181], v[100:103]
	v_mfma_f32_16x16x32_f16 v[88:91], v[154:157], v[198:201], v[88:91]
	v_mfma_f32_16x16x32_f16 v[84:87], v[162:165], v[198:201], v[84:87]
	v_mfma_f32_16x16x32_f16 v[72:75], v[154:157], v[208:211], v[72:75]
	v_mfma_f32_16x16x32_f16 v[68:71], v[162:165], v[208:211], v[68:71]
	v_mfma_f32_16x16x32_f16 v[120:123], v[158:161], v[174:177], v[120:123]
	v_mfma_f32_16x16x32_f16 v[116:119], v[166:169], v[174:177], v[116:119]
	v_mfma_f32_16x16x32_f16 v[104:107], v[158:161], v[190:193], v[104:107]
	v_mfma_f32_16x16x32_f16 v[100:103], v[166:169], v[190:193], v[100:103]
	v_mfma_f32_16x16x32_f16 v[88:91], v[158:161], v[204:207], v[88:91]
	v_mfma_f32_16x16x32_f16 v[84:87], v[166:169], v[204:207], v[84:87]
	v_mfma_f32_16x16x32_f16 v[72:75], v[158:161], v[212:215], v[72:75]
	v_mfma_f32_16x16x32_f16 v[68:71], v[166:169], v[212:215], v[68:71]
	s_setprio 2
	s_barrier
; #define PG8_STAGE(bufoff, gbase, voff, h64) do { \
;         __builtin_amdgcn_global_load_lds((const unsigned*)((const char*)(gbase) + (voff)), (LAS unsigned*)(lds + (bufoff) + ldsw), 16, 0, 0); \
;         __builtin_amdgcn_global_load_lds((const unsigned*)((const char*)(gbase) + (h64) + (voff)), (LAS unsigned*)(lds + (bufoff) + ldsw + 8192), 16, 0, 0); } while (0)
; #define PG8_LDA(dst, b, h) do { _Pragma("unroll") for (int m = 0; m < 4; ++m) { dst[m].lo = *(const LAS f16x8*)(lds + PG8_SA(b, h) + aoff + m * 2048); dst[m].hi = *(const LAS f16x8*)(lds + PG8_SA(b, h) + aoff + m * 2048 + 1024); } } while (0)
; #define PG8_WAIT_V(n) asm volatile("s_waitcnt vmcnt(" #n ")" ::: "memory")
; #define PG8_WAIT_L(n) asm volatile("s_waitcnt lgkmcnt(" #n ")" ::: "memory")
; #define PG8_BAR __builtin_amdgcn_s_barrier()
; #define PG8_SCHED __builtin_amdgcn_sched_barrier(0)
; template <bool F8 = false, class Sched, class Epi>
; __device__ __forceinline__ void gemm_phase(LAS unsigned char* lds, const Sched& S, const Epi& E) {
;     ...
;             PG8_LDA(At, 1, 1); PG8_STAGE(PG8_SB(1, 0), b3, vB2, h2); PG8_STAGE(PG8_SB(1, 1), b3 + bhs2, vB2, h2); PG8_STAGE(PG8_SA(1, 0), a3, vA2, h2);
;             PG8_WAIT_V(8); PG8_WAIT_L(0); PG8_BAR; PG8_MMA(1, 0, At, B0); PG8_MMA(1, 1, At, B1); PG8_BAR; PG8_SCHED;
	s_add_i32 s6, s8, s49
	v_lshl_add_u64 v[136:137], v[182:183], 0, s[40:41]
	s_mov_b32 m0, s6
	ds_read_b128 v[170:173], v202 offset:49152
	ds_read_b128 v[174:177], v202 offset:50176
	ds_read_b128 v[178:181], v202 offset:51200
	ds_read_b128 v[190:193], v202 offset:52224
	ds_read_b128 v[198:201], v202 offset:53248
	ds_read_b128 v[204:207], v202 offset:54272
	ds_read_b128 v[208:211], v202 offset:55296
	ds_read_b128 v[212:215], v202 offset:56320
	global_load_lds_dwordx4 v[136:137], off
	v_lshl_add_u64 v[136:137], v[194:195], 0, s[40:41]
	s_add_i32 m0, s6, 0x2000
	s_add_i32 s6, s9, s49
	global_load_lds_dwordx4 v[136:137], off
	v_lshl_add_u64 v[136:137], v[216:217], 0, s[40:41]
	s_mov_b32 m0, s6
	s_nop 0
	global_load_lds_dwordx4 v[136:137], off
	v_lshl_add_u64 v[136:137], v[234:235], 0, s[40:41]
	s_add_i32 m0, s6, 0x2000
	s_nop 0
	global_load_lds_dwordx4 v[136:137], off
	v_lshl_add_u64 v[136:137], v[236:237], 0, s[40:41]
	s_mov_b32 m0, s92
	s_nop 0
	global_load_lds_dwordx4 v[136:137], off
	v_lshl_add_u64 v[136:137], v[238:239], 0, s[40:41]
	s_mov_b32 m0, s93
	s_nop 0
	global_load_lds_dwordx4 v[136:137], off
	s_waitcnt vmcnt(8)
	s_waitcnt lgkmcnt(0)
	s_barrier
	s_setprio 1
	s_waitcnt lgkmcnt(0)
	v_mfma_f32_16x16x32_f16 v[64:67], v[138:141], v[170:173], v[64:67]
	v_mfma_f32_16x16x32_f16 v[60:63], v[146:149], v[170:173], v[60:63]
	v_mfma_f32_16x16x32_f16 v[48:51], v[138:141], v[178:181], v[48:51]
	v_mfma_f32_16x16x32_f16 v[44:47], v[146:149], v[178:181], v[44:47]
	v_mfma_f32_16x16x32_f16 v[28:31], v[138:141], v[198:201], v[28:31]
	v_mfma_f32_16x16x32_f16 v[24:27], v[146:149], v[198:201], v[24:27]
	v_mfma_f32_16x16x32_f16 v[12:15], v[138:141], v[208:211], v[12:15]
	v_mfma_f32_16x16x32_f16 v[8:11], v[146:149], v[208:211], v[8:11]
	v_mfma_f32_16x16x32_f16 v[64:67], v[142:145], v[174:177], v[64:67]
	v_mfma_f32_16x16x32_f16 v[60:63], v[150:153], v[174:177], v[60:63]
	v_mfma_f32_16x16x32_f16 v[48:51], v[142:145], v[190:193], v[48:51]
	v_mfma_f32_16x16x32_f16 v[44:47], v[150:153], v[190:193], v[44:47]
	v_mfma_f32_16x16x32_f16 v[28:31], v[142:145], v[204:207], v[28:31]
	v_mfma_f32_16x16x32_f16 v[24:27], v[150:153], v[204:207], v[24:27]
	v_mfma_f32_16x16x32_f16 v[12:15], v[142:145], v[212:215], v[12:15]
	v_mfma_f32_16x16x32_f16 v[8:11], v[150:153], v[212:215], v[8:11]
	s_setprio 0
	s_setprio 1
	v_mfma_f32_16x16x32_f16 v[56:59], v[154:157], v[170:173], v[56:59]
	v_mfma_f32_16x16x32_f16 v[52:55], v[162:165], v[170:173], v[52:55]
	v_mfma_f32_16x16x32_f16 v[40:43], v[154:157], v[178:181], v[40:43]
	v_mfma_f32_16x16x32_f16 v[36:39], v[162:165], v[178:181], v[36:39]
	v_mfma_f32_16x16x32_f16 v[20:23], v[154:157], v[198:201], v[20:23]
	v_mfma_f32_16x16x32_f16 v[16:19], v[162:165], v[198:201], v[16:19]
	v_mfma_f32_16x16x32_f16 v[4:7], v[154:157], v[208:211], v[4:7]
	v_mfma_f32_16x16x32_f16 v[0:3], v[162:165], v[208:211], v[0:3]
	v_mfma_f32_16x16x32_f16 v[56:59], v[158:161], v[174:177], v[56:59]
	v_mfma_f32_16x16x32_f16 v[52:55], v[166:169], v[174:177], v[52:55]
	v_mfma_f32_16x16x32_f16 v[40:43], v[158:161], v[190:193], v[40:43]
	v_mfma_f32_16x16x32_f16 v[36:39], v[166:169], v[190:193], v[36:39]
	v_mfma_f32_16x16x32_f16 v[20:23], v[158:161], v[204:207], v[20:23]
	v_mfma_f32_16x16x32_f16 v[16:19], v[166:169], v[204:207], v[16:19]
	v_mfma_f32_16x16x32_f16 v[4:7], v[158:161], v[212:215], v[4:7]
	v_mfma_f32_16x16x32_f16 v[0:3], v[166:169], v[212:215], v[0:3]
	s_setprio 2
	s_barrier
	s_add_u32 s10, s10, 0x100
	s_addc_u32 s11, s11, 0
	s_cmp_ge_u32 s79, s36
	s_cbranch_scc1 .LBB0_217
